# P4 pipelined (aligned), O/G loads nontemporal
# speedup vs baseline: 1.0102x; 1.0102x over previous
; __device__ __forceinline__ float wave_sum(float v) {
; #pragma unroll
;     for (int o = 1; o < 64; o <<= 1) v += __shfl_xor(v, o);
;     return v;
; __device__ __forceinline__ void p4_gn_gate(Frame& F) {
;     const int gw = F.vcu * NWAVES + F.wave, NGW = F.G * NWAVES;
;     const bf16* O = WSP(bf16, WS_O); const bf16* G = WSP(bf16, WS_G); bf16* A2 = WSP(bf16, WS_A2);
;     for (int t = gw; t < M * NH; t += NGW) {
;         const int r = t >> 3, h = t & 7; const size_t off = (size_t)r * HV + h * DV + 8 * F.lane;
;         const u32x4 ov = *(const u32x4*)(O + off), gv = *(const u32x4*)(G + off);
;         float o[8], g[8];
; #pragma unroll
;         for (int i = 0; i < 4; ++i) { o[2 * i] = __uint_as_float(ov[i] << 16); o[2 * i + 1] = __uint_as_float(ov[i] & 0xffff0000u); g[2 * i] = __uint_as_float(gv[i] << 16); g[2 * i + 1] = __uint_as_float(gv[i] & 0xffff0000u); }
.LBB0_729:
	v_readlane_b32 s2, v240, 0
	v_readlane_b32 s3, v240, 1
	s_cmp_lt_i32 s2, 5
	s_cselect_b64 s[2:3], -1, 0
	s_and_b64 s[2:3], s[2:3], s[0:1]
	s_mov_b32 s0, s44
	s_andn2_b64 vcc, exec, s[2:3]
	v_writelane_b32 v240, s0, 44
	s_nop 1
	v_writelane_b32 v240, s1, 45
	s_cbranch_vccnz .LBB0_733
	v_readlane_b32 s0, v240, 5
	v_readlane_b32 s1, v240, 6
	s_lshl_b32 s0, s0, 3
	v_readlane_b32 s1, v240, 43
	s_add_i32 s10, s0, s1
	s_cmp_gt_i32 s10, 0x11fff
	s_cbranch_scc1 .LBB0_733
	v_mbcnt_lo_u32_b32 v1, -1, 0
	v_mbcnt_hi_u32_b32 v2, -1, v1
	v_and_b32_e32 v1, 64, v2
	s_waitcnt vmcnt(0)
	v_add_u32_e32 v4, 64, v1
	v_xor_b32_e32 v1, 1, v2
	v_cmp_lt_i32_e32 vcc, v1, v4
	v_xor_b32_e32 v3, 2, v2
	v_xor_b32_e32 v5, 4, v2
	v_cndmask_b32_e32 v1, v2, v1, vcc
	v_cmp_lt_i32_e32 vcc, v3, v4
	s_lshl_b32 s16, s44, 3
	s_add_u32 s4, s30, 0x1d400000
	v_cndmask_b32_e32 v3, v2, v3, vcc
	v_cmp_lt_i32_e32 vcc, v5, v4
	s_addc_u32 s5, s31, 0
	s_add_u32 s6, s30, 0x18c00000
	v_cndmask_b32_e32 v5, v2, v5, vcc
	v_lshlrev_b32_e32 v6, 2, v5
	v_xor_b32_e32 v5, 8, v2
	v_cmp_lt_i32_e32 vcc, v5, v4
	v_readlane_b32 s0, v240, 5
	s_addc_u32 s7, s31, 0
	v_cndmask_b32_e32 v5, v2, v5, vcc
	v_lshlrev_b32_e32 v7, 2, v5
	v_xor_b32_e32 v5, 16, v2
	v_cmp_lt_i32_e32 vcc, v5, v4
	v_readlane_b32 s36, v240, 7
	v_readlane_b32 s1, v240, 6
	v_cndmask_b32_e32 v5, v2, v5, vcc
	v_lshlrev_b32_e32 v8, 2, v5
	v_xor_b32_e32 v5, 32, v2
	s_add_u32 s8, s30, 0x21c00000
	v_cmp_lt_i32_e32 vcc, v5, v4
	v_readlane_b32 s44, v240, 15
	v_readlane_b32 s45, v240, 16
	v_readlane_b32 s1, v240, 43
	s_addc_u32 s9, s31, 0
	v_cndmask_b32_e32 v2, v2, v5, vcc
	v_mov_b32_e32 v5, 0
	v_lshlrev_b32_e32 v4, 5, v220
	v_readlane_b32 s42, v240, 13
	v_readlane_b32 s43, v240, 14
	v_readlane_b32 s44, v240, 44
	s_lshl_b32 s0, s0, 12
	s_lshl_b32 s1, s1, 9
	s_mov_b32 s15, 0
	v_lshlrev_b32_e32 v1, 2, v1
	v_lshlrev_b32_e32 v3, 2, v3
	v_lshlrev_b32_e32 v9, 2, v2
	v_lshlrev_b32_e32 v2, 3, v220
	v_lshl_add_u64 v[4:5], s[42:43], 0, v[4:5]
	s_add_i32 s17, s0, s1
	s_lshl_b32 s18, s44, 12
	v_mov_b32_e32 v10, 0x358637bd
	s_mov_b32 s19, 0xf800000
	v_mov_b32_e32 v11, 0x260
	s_mov_b32 s20, 0xc3dc0000
	v_mov_b32_e32 v12, 0x43dc0000
	v_readlane_b32 s37, v240, 8
	v_readlane_b32 s38, v240, 9
	v_readlane_b32 s39, v240, 10
	v_readlane_b32 s40, v240, 11
	v_readlane_b32 s41, v240, 12
	v_readlane_b32 s46, v240, 17
	v_readlane_b32 s47, v240, 18
	v_readlane_b32 s48, v240, 19
	v_readlane_b32 s49, v240, 20
	v_readlane_b32 s50, v240, 21
	v_readlane_b32 s51, v240, 22
	v_readlane_b32 s45, v240, 45
	v_readlane_b32 s0, v240, 43
	s_and_b32 s21, s17, 0xe00
	v_lshlrev_b32_e32 v13, 1, v2
	s_nop 1
	s_lshl_b32 s0, s0, 10
	v_add_u32_e32 v15, s21, v2
	v_add_u32_e32 v14, s0, v13
	s_lshl_b32 s14, s21, 2
	ds_write_b128 v14, v[48:51]
	ds_write_b128 v14, v[52:55] offset:8192
	ds_write_b128 v14, v[56:59] offset:16384
	ds_write_b128 v14, v[60:63] offset:24576
	ds_write_b128 v14, v[64:67] offset:32768
	v_lshlrev_b32_e32 v13, 1, v15
	v_lshl_add_u64 v[44:45], v[4:5], 0, s[14:15]
	s_mov_b32 s1, s10
	s_waitcnt lgkmcnt(0)
	global_load_dwordx4 v[216:219], v[44:45], off offset:16
	global_load_dwordx4 v[212:215], v[44:45], off
	s_min_u32 s0, s1, 0x11fff
	s_lshr_b32 s0, s0, 3
	s_lshl_b32 s0, s0, 13
	s_add_u32 s32, s4, s0
	s_addc_u32 s33, s5, 0
	s_add_u32 s40, s6, s0
	s_addc_u32 s41, s7, 0
	global_load_dwordx4 v[16:19], v13, s[32:33] nt
	global_load_dwordx4 v[20:23], v13, s[40:41] nt
	s_add_i32 s1, s1, s16
	s_min_u32 s0, s1, 0x11fff
	s_lshr_b32 s0, s0, 3
	s_lshl_b32 s0, s0, 13
	s_add_u32 s32, s4, s0
	s_addc_u32 s33, s5, 0
	s_add_u32 s40, s6, s0
	s_addc_u32 s41, s7, 0
	global_load_dwordx4 v[24:27], v13, s[32:33] nt
	global_load_dwordx4 v[28:31], v13, s[40:41] nt
	s_add_i32 s1, s1, s16
	s_min_u32 s0, s1, 0x11fff
	s_lshr_b32 s0, s0, 3
	s_lshl_b32 s0, s0, 13
	s_add_u32 s32, s4, s0
	s_addc_u32 s33, s5, 0
	s_add_u32 s40, s6, s0
	s_addc_u32 s41, s7, 0
	global_load_dwordx4 v[32:35], v13, s[32:33] nt
	global_load_dwordx4 v[36:39], v13, s[40:41] nt
	global_load_dwordx4 v[32:35], v13, s[32:33] nt
	global_load_dwordx4 v[36:39], v13, s[40:41] nt
	s_add_i32 s1, s1, s16
	s_min_u32 s0, s1, 0x11fff
	s_lshr_b32 s0, s0, 3
	s_lshl_b32 s0, s0, 13
	s_add_u32 s32, s4, s0
	s_addc_u32 s33, s5, 0
	s_add_u32 s40, s6, s0
	s_addc_u32 s41, s7, 0
	global_load_dwordx4 v[40:43], v13, s[32:33] nt
	global_load_dwordx4 v[48:51], v13, s[40:41] nt
	s_add_i32 s1, s1, s16
	s_min_u32 s0, s1, 0x11fff
	s_lshr_b32 s0, s0, 3
	s_lshl_b32 s0, s0, 13
	s_add_u32 s32, s4, s0
	s_addc_u32 s33, s5, 0
	s_add_u32 s40, s6, s0
	s_addc_u32 s41, s7, 0
	global_load_dwordx4 v[52:55], v13, s[32:33] nt
	global_load_dwordx4 v[56:59], v13, s[40:41] nt
	global_load_dwordx4 v[52:55], v13, s[32:33] nt
	global_load_dwordx4 v[56:59], v13, s[40:41] nt
	s_add_i32 s1, s1, s16
	s_min_u32 s0, s1, 0x11fff
	s_lshr_b32 s0, s0, 3
	s_lshl_b32 s0, s0, 13
	s_add_u32 s32, s4, s0
	s_addc_u32 s33, s5, 0
	s_add_u32 s40, s6, s0
	s_addc_u32 s41, s7, 0
	global_load_dwordx4 v[60:63], v13, s[32:33] nt
	global_load_dwordx4 v[64:67], v13, s[40:41] nt
	s_add_i32 s1, s1, s16
; __device__ __forceinline__ void p4_gn_gate(Frame& F) {
;     ...
;     for (int t = gw; t < M * NH; t += NGW) {
;         const int r = t >> 3, h = t & 7; const size_t off = (size_t)r * HV + h * DV + 8 * F.lane;
;         const u32x4 ov = *(const u32x4*)(O + off), gv = *(const u32x4*)(G + off);
;         float o[8], g[8];
; #pragma unroll
;         for (int i = 0; i < 4; ++i) { o[2 * i] = __uint_as_float(ov[i] << 16); o[2 * i + 1] = __uint_as_float(ov[i] & 0xffff0000u); g[2 * i] = __uint_as_float(gv[i] << 16); g[2 * i + 1] = __uint_as_float(gv[i] & 0xffff0000u); }
;         float s = 0.f;
; #pragma unroll
;         for (int i = 0; i < 8; ++i) s += o[i];
;         const float mu = wave_sum(s) * (1.0f / DV); float q = 0.f;
; #pragma unroll
.Lp4_loop:
	s_cmp_lt_i32 s10, 0x12000
	s_cbranch_scc0 .Lp4_done
	s_min_u32 s0, s10, 0x11fff
	s_lshr_b32 s0, s0, 3
	s_lshl_b32 s0, s0, 12
	s_add_u32 s46, s8, s0
	s_addc_u32 s47, s9, 0
	s_add_i32 s14, s10, s16
	s_min_u32 s14, s14, 0x11fff
	s_lshr_b32 s14, s14, 3
	s_lshl_b32 s14, s14, 12
	s_add_u32 s50, s8, s14
	s_addc_u32 s51, s9, 0
	s_waitcnt vmcnt(12)
	v_lshlrev_b32_e32 v224, 16, v16
	v_lshlrev_b32_e32 v232, 16, v24
	v_and_b32_e32 v16, 0xffff0000, v16
	v_and_b32_e32 v24, 0xffff0000, v24
	v_add_f32_e32 v143, 0, v224
	v_add_f32_e32 v210, 0, v232
	v_lshlrev_b32_e32 v225, 16, v17
	v_lshlrev_b32_e32 v233, 16, v25
	v_add_f32_e32 v143, v143, v16
	v_add_f32_e32 v210, v210, v24
	v_and_b32_e32 v17, 0xffff0000, v17
	v_and_b32_e32 v25, 0xffff0000, v25
	v_add_f32_e32 v143, v143, v225
	v_add_f32_e32 v210, v210, v233
	v_lshlrev_b32_e32 v226, 16, v18
	v_lshlrev_b32_e32 v234, 16, v26
	v_add_f32_e32 v143, v143, v17
	v_add_f32_e32 v210, v210, v25
	v_and_b32_e32 v18, 0xffff0000, v18
	v_and_b32_e32 v26, 0xffff0000, v26
	v_add_f32_e32 v143, v143, v226
	v_add_f32_e32 v210, v210, v234
	v_lshlrev_b32_e32 v227, 16, v19
	v_lshlrev_b32_e32 v235, 16, v27
	v_add_f32_e32 v143, v143, v18
	v_add_f32_e32 v210, v210, v26
	v_and_b32_e32 v19, 0xffff0000, v19
	v_and_b32_e32 v27, 0xffff0000, v27
	v_add_f32_e32 v143, v143, v227
	v_add_f32_e32 v210, v210, v235
	v_add_f32_e32 v143, v143, v19
	v_add_f32_e32 v210, v210, v27
	ds_bpermute_b32 v153, v1, v143
	ds_bpermute_b32 v211, v1, v210
	v_lshlrev_b32_e32 v228, 16, v20
	v_lshlrev_b32_e32 v236, 16, v28
	v_and_b32_e32 v20, 0xffff0000, v20
	s_waitcnt lgkmcnt(1)
	v_add_f32_e32 v143, v143, v153
	s_waitcnt lgkmcnt(0)
	v_add_f32_e32 v210, v210, v211
	ds_bpermute_b32 v153, v3, v143
	ds_bpermute_b32 v211, v3, v210
	v_and_b32_e32 v28, 0xffff0000, v28
	v_lshlrev_b32_e32 v229, 16, v21
	v_lshlrev_b32_e32 v237, 16, v29
	s_waitcnt lgkmcnt(1)
	v_add_f32_e32 v143, v143, v153
	s_waitcnt lgkmcnt(0)
	v_add_f32_e32 v210, v210, v211
	ds_bpermute_b32 v153, v6, v143
	ds_bpermute_b32 v211, v6, v210
	v_and_b32_e32 v21, 0xffff0000, v21
	v_and_b32_e32 v29, 0xffff0000, v29
	v_lshlrev_b32_e32 v230, 16, v22
	s_waitcnt lgkmcnt(1)
	v_add_f32_e32 v143, v143, v153
	s_waitcnt lgkmcnt(0)
	v_add_f32_e32 v210, v210, v211
	ds_bpermute_b32 v153, v7, v143
	ds_bpermute_b32 v211, v7, v210
	v_lshlrev_b32_e32 v238, 16, v30
	v_and_b32_e32 v22, 0xffff0000, v22
	v_and_b32_e32 v30, 0xffff0000, v30
	s_waitcnt lgkmcnt(1)
	v_add_f32_e32 v143, v143, v153
	s_waitcnt lgkmcnt(0)
	v_add_f32_e32 v210, v210, v211
	ds_bpermute_b32 v153, v8, v143
	ds_bpermute_b32 v211, v8, v210
	v_lshlrev_b32_e32 v231, 16, v23
	v_lshlrev_b32_e32 v239, 16, v31
	v_and_b32_e32 v23, 0xffff0000, v23
	s_waitcnt lgkmcnt(1)
	v_add_f32_e32 v143, v143, v153
	s_waitcnt lgkmcnt(0)
	v_add_f32_e32 v210, v210, v211
	ds_bpermute_b32 v153, v9, v143
	ds_bpermute_b32 v211, v9, v210
	v_and_b32_e32 v31, 0xffff0000, v31
	s_waitcnt lgkmcnt(1)
	v_add_f32_e32 v143, v143, v153
	s_waitcnt lgkmcnt(0)
	v_add_f32_e32 v210, v210, v211
	v_fmac_f32_e32 v16, 0xbb000000, v143
	v_fmac_f32_e32 v24, 0xbb000000, v210
	v_fmac_f32_e32 v224, 0xbb000000, v143
	v_fmac_f32_e32 v232, 0xbb000000, v210
	v_fmac_f32_e32 v225, 0xbb000000, v143
	v_fmac_f32_e32 v233, 0xbb000000, v210
	v_fmac_f32_e32 v17, 0xbb000000, v143
	v_fmac_f32_e32 v25, 0xbb000000, v210
	v_fmac_f32_e32 v226, 0xbb000000, v143
	v_fmac_f32_e32 v234, 0xbb000000, v210
	v_fmac_f32_e32 v18, 0xbb000000, v143
	v_fmac_f32_e32 v26, 0xbb000000, v210
	v_fmac_f32_e32 v227, 0xbb000000, v143
	v_fmac_f32_e32 v235, 0xbb000000, v210
	v_fmac_f32_e32 v19, 0xbb000000, v143
	v_fmac_f32_e32 v27, 0xbb000000, v210
	v_mul_f32_e32 v143, v16, v16
	v_mul_f32_e32 v210, v24, v24
	v_fmac_f32_e32 v143, v224, v224
	v_fmac_f32_e32 v210, v232, v232
	v_fmac_f32_e32 v143, v225, v225
	v_fmac_f32_e32 v210, v233, v233
	v_fmac_f32_e32 v143, v17, v17
	v_fmac_f32_e32 v210, v25, v25
	v_fmac_f32_e32 v143, v226, v226
	v_fmac_f32_e32 v210, v234, v234
	v_fmac_f32_e32 v143, v18, v18
	v_fmac_f32_e32 v210, v26, v26
	v_fmac_f32_e32 v143, v227, v227
	v_fmac_f32_e32 v210, v235, v235
	v_fmac_f32_e32 v143, v19, v19
	v_fmac_f32_e32 v210, v27, v27
	ds_bpermute_b32 v153, v1, v143
	ds_bpermute_b32 v211, v1, v210
	s_waitcnt lgkmcnt(1)
	v_add_f32_e32 v143, v143, v153
	s_waitcnt lgkmcnt(0)
	v_add_f32_e32 v210, v210, v211
	ds_bpermute_b32 v153, v3, v143
	ds_bpermute_b32 v211, v3, v210
	s_waitcnt lgkmcnt(1)
	v_add_f32_e32 v143, v143, v153
	s_waitcnt lgkmcnt(0)
	v_add_f32_e32 v210, v210, v211
	ds_bpermute_b32 v153, v6, v143
	ds_bpermute_b32 v211, v6, v210
	s_waitcnt lgkmcnt(1)
	v_add_f32_e32 v143, v143, v153
	s_waitcnt lgkmcnt(0)
	v_add_f32_e32 v210, v210, v211
	ds_bpermute_b32 v153, v7, v143
	ds_bpermute_b32 v211, v7, v210
	s_waitcnt lgkmcnt(1)
	v_add_f32_e32 v143, v143, v153
	s_waitcnt lgkmcnt(0)
	v_add_f32_e32 v210, v210, v211
	ds_bpermute_b32 v153, v8, v143
	ds_bpermute_b32 v211, v8, v210
	s_waitcnt lgkmcnt(1)
	v_add_f32_e32 v143, v143, v153
	s_waitcnt lgkmcnt(0)
	v_add_f32_e32 v210, v210, v211
	ds_bpermute_b32 v153, v9, v143
	ds_bpermute_b32 v211, v9, v210
	s_waitcnt lgkmcnt(1)
	v_add_f32_e32 v143, v143, v153
	s_waitcnt lgkmcnt(0)
; __device__ __forceinline__ void p4_gn_gate(Frame& F) {
;     ...
;         const int r = t >> 3, h = t & 7; const size_t off = (size_t)r * HV + h * DV + 8 * F.lane;
;         const u32x4 ov = *(const u32x4*)(O + off), gv = *(const u32x4*)(G + off);
;     ...
;         const float rstd = 1.0f / sqrtf(wave_sum(q) * (1.0f / DV) + 1e-6f);
;         const f32x4 w0 = *(const f32x4*)(F.ret_gn_g + h * DV + 8 * F.lane), w1 = *(const f32x4*)(F.ret_gn_g + h * DV + 8 * F.lane + 4);
;         float y[8];
; #pragma unroll
;         for (int i = 0; i < 4; ++i) { y[i] = g[i] * (o[i] * rstd * w0[i]); y[i + 4] = g[i + 4] * (o[i + 4] * rstd * w1[i]); }
;         if (FP8O) { u32x2 out; out.x = pk4_fp8(y[0] * S_A2, y[1] * S_A2, y[2] * S_A2, y[3] * S_A2); out.y = pk4_fp8(y[4] * S_A2, y[5] * S_A2, y[6] * S_A2, y[7] * S_A2); *(u32x2*)((unsigned char*)A2 + off) = out; }
	v_add_f32_e32 v210, v210, v211
	v_fmamk_f32 v143, v143, 0x3b000000, v10
	v_mul_f32_e32 v153, 0x4f800000, v143
	v_cmp_gt_f32_e32 vcc, s19, v143
	s_nop 1
	v_cndmask_b32_e32 v143, v143, v153, vcc
	v_sqrt_f32_e32 v153, v143
	s_nop 0
	v_add_u32_e32 v155, -1, v153
	v_add_u32_e32 v159, 1, v153
	v_fma_f32 v221, -v155, v153, v143
	v_fma_f32 v46, -v159, v153, v143
	v_cmp_ge_f32_e64 s[56:57], 0, v221
	s_nop 1
	v_cndmask_b32_e64 v153, v153, v155, s[56:57]
	v_cmp_lt_f32_e64 s[56:57], 0, v46
	s_nop 1
	v_cndmask_b32_e64 v153, v153, v159, s[56:57]
	v_mul_f32_e32 v155, 0x37800000, v153
	v_cndmask_b32_e32 v153, v153, v155, vcc
	v_cmp_class_f32_e32 vcc, v143, v11
	s_nop 1
	v_cndmask_b32_e32 v143, v153, v143, vcc
	v_div_scale_f32 v153, s[56:57], v143, v143, 1.0
	v_rcp_f32_e32 v159, v153
	v_div_scale_f32 v155, vcc, 1.0, v143, 1.0
	v_fma_f32 v221, -v153, v159, 1.0
	v_fmac_f32_e32 v159, v221, v159
	v_mul_f32_e32 v221, v155, v159
	v_fma_f32 v46, -v153, v221, v155
	v_fmac_f32_e32 v221, v46, v159
	v_fma_f32 v153, -v153, v221, v155
	v_div_fmas_f32 v153, v153, v159, v221
	v_div_fixup_f32 v143, v153, v143, 1.0
	v_fmamk_f32 v210, v210, 0x3b000000, v10
	v_mul_f32_e32 v211, 0x4f800000, v210
	v_cmp_gt_f32_e32 vcc, s19, v210
	s_nop 1
	v_cndmask_b32_e32 v210, v210, v211, vcc
	v_sqrt_f32_e32 v211, v210
	s_nop 0
	v_add_u32_e32 v192, -1, v211
	v_add_u32_e32 v193, 1, v211
	v_fma_f32 v222, -v192, v211, v210
	v_fma_f32 v223, -v193, v211, v210
	v_cmp_ge_f32_e64 s[58:59], 0, v222
	s_nop 1
	v_cndmask_b32_e64 v211, v211, v192, s[58:59]
	v_cmp_lt_f32_e64 s[58:59], 0, v223
	s_nop 1
	v_cndmask_b32_e64 v211, v211, v193, s[58:59]
	v_mul_f32_e32 v192, 0x37800000, v211
	v_cndmask_b32_e32 v211, v211, v192, vcc
	v_cmp_class_f32_e32 vcc, v210, v11
	s_nop 1
	v_cndmask_b32_e32 v210, v211, v210, vcc
	v_div_scale_f32 v211, s[58:59], v210, v210, 1.0
	v_rcp_f32_e32 v193, v211
	v_div_scale_f32 v192, vcc, 1.0, v210, 1.0
	v_fma_f32 v222, -v211, v193, 1.0
	v_fmac_f32_e32 v193, v222, v193
	v_mul_f32_e32 v222, v192, v193
	v_fma_f32 v223, -v211, v222, v192
	v_fmac_f32_e32 v222, v223, v193
	v_fma_f32 v211, -v211, v222, v192
	v_div_fmas_f32 v211, v211, v193, v222
	v_div_fixup_f32 v210, v211, v210, 1.0
	v_mul_f32_e32 v224, v224, v143
	v_mul_f32_e32 v232, v232, v210
	v_mul_f32_e32 v16, v16, v143
	v_mul_f32_e32 v24, v24, v210
	v_mul_f32_e32 v226, v226, v143
	v_mul_f32_e32 v234, v234, v210
	v_mul_f32_e32 v18, v18, v143
	v_mul_f32_e32 v26, v26, v210
	v_mul_f32_e32 v224, v212, v224
	v_mul_f32_e32 v232, v212, v232
	v_mul_f32_e32 v16, v213, v16
	v_mul_f32_e32 v24, v213, v24
	v_mul_f32_e32 v226, v216, v226
	v_mul_f32_e32 v234, v216, v234
	v_mul_f32_e32 v18, v217, v18
	v_mul_f32_e32 v26, v217, v26
	v_mul_f32_e32 v224, v224, v228
	v_mul_f32_e32 v232, v232, v236
	v_mul_f32_e32 v16, v16, v20
	v_mul_f32_e32 v24, v24, v28
	v_mul_f32_e32 v226, v226, v230
	v_mul_f32_e32 v234, v234, v238
	v_mul_f32_e32 v18, v18, v22
	v_mul_f32_e32 v26, v26, v30
	v_mul_f32_e32 v224, 0x41000000, v224
	v_mul_f32_e32 v232, 0x41000000, v232
	v_mul_f32_e32 v16, 0x41000000, v16
	v_mul_f32_e32 v24, 0x41000000, v24
	v_mul_f32_e32 v226, 0x41000000, v226
	v_mul_f32_e32 v234, 0x41000000, v234
	v_mul_f32_e32 v18, 0x41000000, v18
	v_mul_f32_e32 v26, 0x41000000, v26
	v_med3_f32 v224, v224, s20, v12
	v_med3_f32 v232, v232, s20, v12
	v_med3_f32 v16, v16, s20, v12
	v_med3_f32 v24, v24, s20, v12
	v_med3_f32 v226, v226, s20, v12
	v_med3_f32 v234, v234, s20, v12
	v_med3_f32 v18, v18, s20, v12
	v_med3_f32 v26, v26, s20, v12
	v_cvt_pk_fp8_f32 v44, v224, v16
	v_cvt_pk_fp8_f32 v70, v232, v24
	v_cvt_pk_fp8_f32 v45, v226, v18
	v_cvt_pk_fp8_f32 v71, v234, v26
	v_mul_f32_e32 v225, v225, v143
	v_mul_f32_e32 v233, v233, v210
	v_mul_f32_e32 v17, v17, v143
	v_mul_f32_e32 v25, v25, v210
	v_mul_f32_e32 v227, v227, v143
	v_mul_f32_e32 v235, v235, v210
	v_mul_f32_e32 v19, v19, v143
	v_mul_f32_e32 v27, v27, v210
	v_mul_f32_e32 v225, v214, v225
	v_mul_f32_e32 v233, v214, v233
	v_mul_f32_e32 v17, v215, v17
	v_mul_f32_e32 v25, v215, v25
	v_mul_f32_e32 v227, v218, v227
	v_mul_f32_e32 v235, v218, v235
	v_mul_f32_e32 v19, v219, v19
	v_mul_f32_e32 v27, v219, v27
	v_mul_f32_e32 v225, v225, v229
	v_mul_f32_e32 v233, v233, v237
	v_mul_f32_e32 v17, v17, v21
	v_mul_f32_e32 v25, v25, v29
	v_mul_f32_e32 v227, v227, v231
	v_mul_f32_e32 v235, v235, v239
	v_mul_f32_e32 v19, v19, v23
	v_mul_f32_e32 v27, v27, v31
	v_mul_f32_e32 v225, 0x41000000, v225
	v_mul_f32_e32 v233, 0x41000000, v233
	v_mul_f32_e32 v17, 0x41000000, v17
	v_mul_f32_e32 v25, 0x41000000, v25
	v_mul_f32_e32 v227, 0x41000000, v227
	v_mul_f32_e32 v235, 0x41000000, v235
	v_mul_f32_e32 v19, 0x41000000, v19
	v_mul_f32_e32 v27, 0x41000000, v27
	v_med3_f32 v225, v225, s20, v12
	v_med3_f32 v233, v233, s20, v12
	v_med3_f32 v17, v17, s20, v12
	v_med3_f32 v25, v25, s20, v12
	v_med3_f32 v227, v227, s20, v12
	v_med3_f32 v235, v235, s20, v12
	v_med3_f32 v19, v19, s20, v12
	v_med3_f32 v27, v27, s20, v12
	v_cvt_pk_fp8_f32 v44, v225, v17 op_sel:[0,0,1]
	v_cvt_pk_fp8_f32 v70, v233, v25 op_sel:[0,0,1]
	v_cvt_pk_fp8_f32 v45, v227, v19 op_sel:[0,0,1]
	v_cvt_pk_fp8_f32 v71, v235, v27 op_sel:[0,0,1]
	s_add_i32 s10, s10, s16
	s_add_i32 s10, s10, s16
	global_store_dwordx2 v15, v[44:45], s[46:47]
	global_store_dwordx2 v15, v[70:71], s[50:51]
	s_min_u32 s0, s1, 0x11fff
	s_lshr_b32 s0, s0, 3
	s_lshl_b32 s0, s0, 13
	s_add_u32 s32, s4, s0
	s_addc_u32 s33, s5, 0
	s_add_u32 s40, s6, s0
	s_addc_u32 s41, s7, 0
	global_load_dwordx4 v[16:19], v13, s[32:33] nt
	global_load_dwordx4 v[20:23], v13, s[40:41] nt
	s_add_i32 s1, s1, s16
	s_min_u32 s0, s1, 0x11fff
	s_lshr_b32 s0, s0, 3
	s_lshl_b32 s0, s0, 13
	s_add_u32 s32, s4, s0
	s_addc_u32 s33, s5, 0
	s_add_u32 s40, s6, s0
	s_addc_u32 s41, s7, 0
	global_load_dwordx4 v[24:27], v13, s[32:33] nt
	global_load_dwordx4 v[28:31], v13, s[40:41] nt
	s_add_i32 s1, s1, s16
	s_cmp_lt_i32 s10, 0x12000
	s_cbranch_scc0 .Lp4_done
; __device__ __forceinline__ void p4_gn_gate(Frame& F) {
;     ...
;     for (int t = gw; t < M * NH; t += NGW) {
;         const int r = t >> 3, h = t & 7; const size_t off = (size_t)r * HV + h * DV + 8 * F.lane;
;         const u32x4 ov = *(const u32x4*)(O + off), gv = *(const u32x4*)(G + off);
;         float o[8], g[8];
; #pragma unroll
;         for (int i = 0; i < 4; ++i) { o[2 * i] = __uint_as_float(ov[i] << 16); o[2 * i + 1] = __uint_as_float(ov[i] & 0xffff0000u); g[2 * i] = __uint_as_float(gv[i] << 16); g[2 * i + 1] = __uint_as_float(gv[i] & 0xffff0000u); }
;         float s = 0.f;
; #pragma unroll
;         for (int i = 0; i < 8; ++i) s += o[i];
;         const float mu = wave_sum(s) * (1.0f / DV); float q = 0.f;
; #pragma unroll
	s_min_u32 s0, s10, 0x11fff
	s_lshr_b32 s0, s0, 3
	s_lshl_b32 s0, s0, 12
	s_add_u32 s46, s8, s0
	s_addc_u32 s47, s9, 0
	s_add_i32 s14, s10, s16
	s_min_u32 s14, s14, 0x11fff
	s_lshr_b32 s14, s14, 3
	s_lshl_b32 s14, s14, 12
	s_add_u32 s50, s8, s14
	s_addc_u32 s51, s9, 0
	s_waitcnt vmcnt(12)
	v_lshlrev_b32_e32 v224, 16, v32
	v_lshlrev_b32_e32 v232, 16, v40
	v_and_b32_e32 v32, 0xffff0000, v32
	v_and_b32_e32 v40, 0xffff0000, v40
	v_add_f32_e32 v143, 0, v224
	v_add_f32_e32 v210, 0, v232
	v_lshlrev_b32_e32 v225, 16, v33
	v_lshlrev_b32_e32 v233, 16, v41
	v_add_f32_e32 v143, v143, v32
	v_add_f32_e32 v210, v210, v40
	v_and_b32_e32 v33, 0xffff0000, v33
	v_and_b32_e32 v41, 0xffff0000, v41
	v_add_f32_e32 v143, v143, v225
	v_add_f32_e32 v210, v210, v233
	v_lshlrev_b32_e32 v226, 16, v34
	v_lshlrev_b32_e32 v234, 16, v42
	v_add_f32_e32 v143, v143, v33
	v_add_f32_e32 v210, v210, v41
	v_and_b32_e32 v34, 0xffff0000, v34
	v_and_b32_e32 v42, 0xffff0000, v42
	v_add_f32_e32 v143, v143, v226
	v_add_f32_e32 v210, v210, v234
	v_lshlrev_b32_e32 v227, 16, v35
	v_lshlrev_b32_e32 v235, 16, v43
	v_add_f32_e32 v143, v143, v34
	v_add_f32_e32 v210, v210, v42
	v_and_b32_e32 v35, 0xffff0000, v35
	v_and_b32_e32 v43, 0xffff0000, v43
	v_add_f32_e32 v143, v143, v227
	v_add_f32_e32 v210, v210, v235
	v_add_f32_e32 v143, v143, v35
	v_add_f32_e32 v210, v210, v43
	ds_bpermute_b32 v153, v1, v143
	ds_bpermute_b32 v211, v1, v210
	v_lshlrev_b32_e32 v228, 16, v36
	v_lshlrev_b32_e32 v236, 16, v48
	v_and_b32_e32 v36, 0xffff0000, v36
	s_waitcnt lgkmcnt(1)
	v_add_f32_e32 v143, v143, v153
	s_waitcnt lgkmcnt(0)
	v_add_f32_e32 v210, v210, v211
	ds_bpermute_b32 v153, v3, v143
	ds_bpermute_b32 v211, v3, v210
	v_and_b32_e32 v48, 0xffff0000, v48
	v_lshlrev_b32_e32 v229, 16, v37
	v_lshlrev_b32_e32 v237, 16, v49
	s_waitcnt lgkmcnt(1)
	v_add_f32_e32 v143, v143, v153
	s_waitcnt lgkmcnt(0)
	v_add_f32_e32 v210, v210, v211
	ds_bpermute_b32 v153, v6, v143
	ds_bpermute_b32 v211, v6, v210
	v_and_b32_e32 v37, 0xffff0000, v37
	v_and_b32_e32 v49, 0xffff0000, v49
	v_lshlrev_b32_e32 v230, 16, v38
	s_waitcnt lgkmcnt(1)
	v_add_f32_e32 v143, v143, v153
	s_waitcnt lgkmcnt(0)
	v_add_f32_e32 v210, v210, v211
	ds_bpermute_b32 v153, v7, v143
	ds_bpermute_b32 v211, v7, v210
	v_lshlrev_b32_e32 v238, 16, v50
	v_and_b32_e32 v38, 0xffff0000, v38
	v_and_b32_e32 v50, 0xffff0000, v50
	s_waitcnt lgkmcnt(1)
	v_add_f32_e32 v143, v143, v153
	s_waitcnt lgkmcnt(0)
	v_add_f32_e32 v210, v210, v211
	ds_bpermute_b32 v153, v8, v143
	ds_bpermute_b32 v211, v8, v210
	v_lshlrev_b32_e32 v231, 16, v39
	v_lshlrev_b32_e32 v239, 16, v51
	v_and_b32_e32 v39, 0xffff0000, v39
	s_waitcnt lgkmcnt(1)
	v_add_f32_e32 v143, v143, v153
	s_waitcnt lgkmcnt(0)
	v_add_f32_e32 v210, v210, v211
	ds_bpermute_b32 v153, v9, v143
	ds_bpermute_b32 v211, v9, v210
	v_and_b32_e32 v51, 0xffff0000, v51
	s_waitcnt lgkmcnt(1)
	v_add_f32_e32 v143, v143, v153
	s_waitcnt lgkmcnt(0)
	v_add_f32_e32 v210, v210, v211
	v_fmac_f32_e32 v32, 0xbb000000, v143
	v_fmac_f32_e32 v40, 0xbb000000, v210
	v_fmac_f32_e32 v224, 0xbb000000, v143
	v_fmac_f32_e32 v232, 0xbb000000, v210
	v_fmac_f32_e32 v225, 0xbb000000, v143
	v_fmac_f32_e32 v233, 0xbb000000, v210
	v_fmac_f32_e32 v33, 0xbb000000, v143
	v_fmac_f32_e32 v41, 0xbb000000, v210
	v_fmac_f32_e32 v226, 0xbb000000, v143
	v_fmac_f32_e32 v234, 0xbb000000, v210
	v_fmac_f32_e32 v34, 0xbb000000, v143
	v_fmac_f32_e32 v42, 0xbb000000, v210
	v_fmac_f32_e32 v227, 0xbb000000, v143
	v_fmac_f32_e32 v235, 0xbb000000, v210
	v_fmac_f32_e32 v35, 0xbb000000, v143
	v_fmac_f32_e32 v43, 0xbb000000, v210
	v_mul_f32_e32 v143, v32, v32
	v_mul_f32_e32 v210, v40, v40
	v_fmac_f32_e32 v143, v224, v224
	v_fmac_f32_e32 v210, v232, v232
	v_fmac_f32_e32 v143, v225, v225
	v_fmac_f32_e32 v210, v233, v233
	v_fmac_f32_e32 v143, v33, v33
	v_fmac_f32_e32 v210, v41, v41
	v_fmac_f32_e32 v143, v226, v226
	v_fmac_f32_e32 v210, v234, v234
	v_fmac_f32_e32 v143, v34, v34
	v_fmac_f32_e32 v210, v42, v42
	v_fmac_f32_e32 v143, v227, v227
	v_fmac_f32_e32 v210, v235, v235
	v_fmac_f32_e32 v143, v35, v35
	v_fmac_f32_e32 v210, v43, v43
	ds_bpermute_b32 v153, v1, v143
	ds_bpermute_b32 v211, v1, v210
	s_waitcnt lgkmcnt(1)
	v_add_f32_e32 v143, v143, v153
	s_waitcnt lgkmcnt(0)
	v_add_f32_e32 v210, v210, v211
	ds_bpermute_b32 v153, v3, v143
	ds_bpermute_b32 v211, v3, v210
	s_waitcnt lgkmcnt(1)
	v_add_f32_e32 v143, v143, v153
	s_waitcnt lgkmcnt(0)
	v_add_f32_e32 v210, v210, v211
	ds_bpermute_b32 v153, v6, v143
	ds_bpermute_b32 v211, v6, v210
	s_waitcnt lgkmcnt(1)
	v_add_f32_e32 v143, v143, v153
	s_waitcnt lgkmcnt(0)
	v_add_f32_e32 v210, v210, v211
	ds_bpermute_b32 v153, v7, v143
	ds_bpermute_b32 v211, v7, v210
	s_waitcnt lgkmcnt(1)
	v_add_f32_e32 v143, v143, v153
	s_waitcnt lgkmcnt(0)
	v_add_f32_e32 v210, v210, v211
	ds_bpermute_b32 v153, v8, v143
	ds_bpermute_b32 v211, v8, v210
	s_waitcnt lgkmcnt(1)
	v_add_f32_e32 v143, v143, v153
	s_waitcnt lgkmcnt(0)
	v_add_f32_e32 v210, v210, v211
	ds_bpermute_b32 v153, v9, v143
	ds_bpermute_b32 v211, v9, v210
	s_waitcnt lgkmcnt(1)
	v_add_f32_e32 v143, v143, v153
	s_waitcnt lgkmcnt(0)
; __device__ __forceinline__ void p4_gn_gate(Frame& F) {
;     ...
;         const int r = t >> 3, h = t & 7; const size_t off = (size_t)r * HV + h * DV + 8 * F.lane;
;         const u32x4 ov = *(const u32x4*)(O + off), gv = *(const u32x4*)(G + off);
;     ...
;         const float rstd = 1.0f / sqrtf(wave_sum(q) * (1.0f / DV) + 1e-6f);
;         const f32x4 w0 = *(const f32x4*)(F.ret_gn_g + h * DV + 8 * F.lane), w1 = *(const f32x4*)(F.ret_gn_g + h * DV + 8 * F.lane + 4);
;         float y[8];
; #pragma unroll
;         for (int i = 0; i < 4; ++i) { y[i] = g[i] * (o[i] * rstd * w0[i]); y[i + 4] = g[i + 4] * (o[i + 4] * rstd * w1[i]); }
;         if (FP8O) { u32x2 out; out.x = pk4_fp8(y[0] * S_A2, y[1] * S_A2, y[2] * S_A2, y[3] * S_A2); out.y = pk4_fp8(y[4] * S_A2, y[5] * S_A2, y[6] * S_A2, y[7] * S_A2); *(u32x2*)((unsigned char*)A2 + off) = out; }
	v_add_f32_e32 v210, v210, v211
	v_fmamk_f32 v143, v143, 0x3b000000, v10
	v_mul_f32_e32 v153, 0x4f800000, v143
	v_cmp_gt_f32_e32 vcc, s19, v143
	s_nop 1
	v_cndmask_b32_e32 v143, v143, v153, vcc
	v_sqrt_f32_e32 v153, v143
	s_nop 0
	v_add_u32_e32 v155, -1, v153
	v_add_u32_e32 v159, 1, v153
	v_fma_f32 v221, -v155, v153, v143
	v_fma_f32 v46, -v159, v153, v143
	v_cmp_ge_f32_e64 s[56:57], 0, v221
	s_nop 1
	v_cndmask_b32_e64 v153, v153, v155, s[56:57]
	v_cmp_lt_f32_e64 s[56:57], 0, v46
	s_nop 1
	v_cndmask_b32_e64 v153, v153, v159, s[56:57]
	v_mul_f32_e32 v155, 0x37800000, v153
	v_cndmask_b32_e32 v153, v153, v155, vcc
	v_cmp_class_f32_e32 vcc, v143, v11
	s_nop 1
	v_cndmask_b32_e32 v143, v153, v143, vcc
	v_div_scale_f32 v153, s[56:57], v143, v143, 1.0
	v_rcp_f32_e32 v159, v153
	v_div_scale_f32 v155, vcc, 1.0, v143, 1.0
	v_fma_f32 v221, -v153, v159, 1.0
	v_fmac_f32_e32 v159, v221, v159
	v_mul_f32_e32 v221, v155, v159
	v_fma_f32 v46, -v153, v221, v155
	v_fmac_f32_e32 v221, v46, v159
	v_fma_f32 v153, -v153, v221, v155
	v_div_fmas_f32 v153, v153, v159, v221
	v_div_fixup_f32 v143, v153, v143, 1.0
	v_fmamk_f32 v210, v210, 0x3b000000, v10
	v_mul_f32_e32 v211, 0x4f800000, v210
	v_cmp_gt_f32_e32 vcc, s19, v210
	s_nop 1
	v_cndmask_b32_e32 v210, v210, v211, vcc
	v_sqrt_f32_e32 v211, v210
	s_nop 0
	v_add_u32_e32 v192, -1, v211
	v_add_u32_e32 v193, 1, v211
	v_fma_f32 v222, -v192, v211, v210
	v_fma_f32 v223, -v193, v211, v210
	v_cmp_ge_f32_e64 s[58:59], 0, v222
	s_nop 1
	v_cndmask_b32_e64 v211, v211, v192, s[58:59]
	v_cmp_lt_f32_e64 s[58:59], 0, v223
	s_nop 1
	v_cndmask_b32_e64 v211, v211, v193, s[58:59]
	v_mul_f32_e32 v192, 0x37800000, v211
	v_cndmask_b32_e32 v211, v211, v192, vcc
	v_cmp_class_f32_e32 vcc, v210, v11
	s_nop 1
	v_cndmask_b32_e32 v210, v211, v210, vcc
	v_div_scale_f32 v211, s[58:59], v210, v210, 1.0
	v_rcp_f32_e32 v193, v211
	v_div_scale_f32 v192, vcc, 1.0, v210, 1.0
	v_fma_f32 v222, -v211, v193, 1.0
	v_fmac_f32_e32 v193, v222, v193
	v_mul_f32_e32 v222, v192, v193
	v_fma_f32 v223, -v211, v222, v192
	v_fmac_f32_e32 v222, v223, v193
	v_fma_f32 v211, -v211, v222, v192
	v_div_fmas_f32 v211, v211, v193, v222
	v_div_fixup_f32 v210, v211, v210, 1.0
	v_mul_f32_e32 v224, v224, v143
	v_mul_f32_e32 v232, v232, v210
	v_mul_f32_e32 v32, v32, v143
	v_mul_f32_e32 v40, v40, v210
	v_mul_f32_e32 v226, v226, v143
	v_mul_f32_e32 v234, v234, v210
	v_mul_f32_e32 v34, v34, v143
	v_mul_f32_e32 v42, v42, v210
	v_mul_f32_e32 v224, v212, v224
	v_mul_f32_e32 v232, v212, v232
	v_mul_f32_e32 v32, v213, v32
	v_mul_f32_e32 v40, v213, v40
	v_mul_f32_e32 v226, v216, v226
	v_mul_f32_e32 v234, v216, v234
	v_mul_f32_e32 v34, v217, v34
	v_mul_f32_e32 v42, v217, v42
	v_mul_f32_e32 v224, v224, v228
	v_mul_f32_e32 v232, v232, v236
	v_mul_f32_e32 v32, v32, v36
	v_mul_f32_e32 v40, v40, v48
	v_mul_f32_e32 v226, v226, v230
	v_mul_f32_e32 v234, v234, v238
	v_mul_f32_e32 v34, v34, v38
	v_mul_f32_e32 v42, v42, v50
	v_mul_f32_e32 v224, 0x41000000, v224
	v_mul_f32_e32 v232, 0x41000000, v232
	v_mul_f32_e32 v32, 0x41000000, v32
	v_mul_f32_e32 v40, 0x41000000, v40
	v_mul_f32_e32 v226, 0x41000000, v226
	v_mul_f32_e32 v234, 0x41000000, v234
	v_mul_f32_e32 v34, 0x41000000, v34
	v_mul_f32_e32 v42, 0x41000000, v42
	v_med3_f32 v224, v224, s20, v12
	v_med3_f32 v232, v232, s20, v12
	v_med3_f32 v32, v32, s20, v12
	v_med3_f32 v40, v40, s20, v12
	v_med3_f32 v226, v226, s20, v12
	v_med3_f32 v234, v234, s20, v12
	v_med3_f32 v34, v34, s20, v12
	v_med3_f32 v42, v42, s20, v12
	v_cvt_pk_fp8_f32 v44, v224, v32
	v_cvt_pk_fp8_f32 v70, v232, v40
	v_cvt_pk_fp8_f32 v45, v226, v34
	v_cvt_pk_fp8_f32 v71, v234, v42
	v_mul_f32_e32 v225, v225, v143
	v_mul_f32_e32 v233, v233, v210
	v_mul_f32_e32 v33, v33, v143
	v_mul_f32_e32 v41, v41, v210
	v_mul_f32_e32 v227, v227, v143
	v_mul_f32_e32 v235, v235, v210
	v_mul_f32_e32 v35, v35, v143
	v_mul_f32_e32 v43, v43, v210
	v_mul_f32_e32 v225, v214, v225
	v_mul_f32_e32 v233, v214, v233
	v_mul_f32_e32 v33, v215, v33
	v_mul_f32_e32 v41, v215, v41
	v_mul_f32_e32 v227, v218, v227
	v_mul_f32_e32 v235, v218, v235
	v_mul_f32_e32 v35, v219, v35
	v_mul_f32_e32 v43, v219, v43
	v_mul_f32_e32 v225, v225, v229
	v_mul_f32_e32 v233, v233, v237
	v_mul_f32_e32 v33, v33, v37
	v_mul_f32_e32 v41, v41, v49
	v_mul_f32_e32 v227, v227, v231
	v_mul_f32_e32 v235, v235, v239
	v_mul_f32_e32 v35, v35, v39
	v_mul_f32_e32 v43, v43, v51
	v_mul_f32_e32 v225, 0x41000000, v225
	v_mul_f32_e32 v233, 0x41000000, v233
	v_mul_f32_e32 v33, 0x41000000, v33
	v_mul_f32_e32 v41, 0x41000000, v41
	v_mul_f32_e32 v227, 0x41000000, v227
	v_mul_f32_e32 v235, 0x41000000, v235
	v_mul_f32_e32 v35, 0x41000000, v35
	v_mul_f32_e32 v43, 0x41000000, v43
	v_med3_f32 v225, v225, s20, v12
	v_med3_f32 v233, v233, s20, v12
	v_med3_f32 v33, v33, s20, v12
	v_med3_f32 v41, v41, s20, v12
	v_med3_f32 v227, v227, s20, v12
	v_med3_f32 v235, v235, s20, v12
	v_med3_f32 v35, v35, s20, v12
	v_med3_f32 v43, v43, s20, v12
	v_cvt_pk_fp8_f32 v44, v225, v33 op_sel:[0,0,1]
	v_cvt_pk_fp8_f32 v70, v233, v41 op_sel:[0,0,1]
	v_cvt_pk_fp8_f32 v45, v227, v35 op_sel:[0,0,1]
	v_cvt_pk_fp8_f32 v71, v235, v43 op_sel:[0,0,1]
	s_add_i32 s10, s10, s16
	s_add_i32 s10, s10, s16
	global_store_dwordx2 v15, v[44:45], s[46:47]
	global_store_dwordx2 v15, v[70:71], s[50:51]
	s_min_u32 s0, s1, 0x11fff
	s_lshr_b32 s0, s0, 3
	s_lshl_b32 s0, s0, 13
	s_add_u32 s32, s4, s0
	s_addc_u32 s33, s5, 0
	s_add_u32 s40, s6, s0
	s_addc_u32 s41, s7, 0
	global_load_dwordx4 v[32:35], v13, s[32:33] nt
	global_load_dwordx4 v[36:39], v13, s[40:41] nt
	s_add_i32 s1, s1, s16
	s_min_u32 s0, s1, 0x11fff
	s_lshr_b32 s0, s0, 3
	s_lshl_b32 s0, s0, 13
	s_add_u32 s32, s4, s0
	s_addc_u32 s33, s5, 0
	s_add_u32 s40, s6, s0
	s_addc_u32 s41, s7, 0
	global_load_dwordx4 v[40:43], v13, s[32:33] nt
	global_load_dwordx4 v[48:51], v13, s[40:41] nt
	s_add_i32 s1, s1, s16
	s_cmp_lt_i32 s10, 0x12000
	s_cbranch_scc0 .Lp4_done
; __device__ __forceinline__ void p4_gn_gate(Frame& F) {
;     ...
;     for (int t = gw; t < M * NH; t += NGW) {
;         const int r = t >> 3, h = t & 7; const size_t off = (size_t)r * HV + h * DV + 8 * F.lane;
;         const u32x4 ov = *(const u32x4*)(O + off), gv = *(const u32x4*)(G + off);
;         float o[8], g[8];
; #pragma unroll
;         for (int i = 0; i < 4; ++i) { o[2 * i] = __uint_as_float(ov[i] << 16); o[2 * i + 1] = __uint_as_float(ov[i] & 0xffff0000u); g[2 * i] = __uint_as_float(gv[i] << 16); g[2 * i + 1] = __uint_as_float(gv[i] & 0xffff0000u); }
;         float s = 0.f;
; #pragma unroll
;         for (int i = 0; i < 8; ++i) s += o[i];
;         const float mu = wave_sum(s) * (1.0f / DV); float q = 0.f;
; #pragma unroll
	s_min_u32 s0, s10, 0x11fff
	s_lshr_b32 s0, s0, 3
	s_lshl_b32 s0, s0, 12
	s_add_u32 s46, s8, s0
	s_addc_u32 s47, s9, 0
	s_add_i32 s14, s10, s16
	s_min_u32 s14, s14, 0x11fff
	s_lshr_b32 s14, s14, 3
	s_lshl_b32 s14, s14, 12
	s_add_u32 s50, s8, s14
	s_addc_u32 s51, s9, 0
	s_waitcnt vmcnt(12)
	v_lshlrev_b32_e32 v224, 16, v52
	v_lshlrev_b32_e32 v232, 16, v60
	v_and_b32_e32 v52, 0xffff0000, v52
	v_and_b32_e32 v60, 0xffff0000, v60
	v_add_f32_e32 v143, 0, v224
	v_add_f32_e32 v210, 0, v232
	v_lshlrev_b32_e32 v225, 16, v53
	v_lshlrev_b32_e32 v233, 16, v61
	v_add_f32_e32 v143, v143, v52
	v_add_f32_e32 v210, v210, v60
	v_and_b32_e32 v53, 0xffff0000, v53
	v_and_b32_e32 v61, 0xffff0000, v61
	v_add_f32_e32 v143, v143, v225
	v_add_f32_e32 v210, v210, v233
	v_lshlrev_b32_e32 v226, 16, v54
	v_lshlrev_b32_e32 v234, 16, v62
	v_add_f32_e32 v143, v143, v53
	v_add_f32_e32 v210, v210, v61
	v_and_b32_e32 v54, 0xffff0000, v54
	v_and_b32_e32 v62, 0xffff0000, v62
	v_add_f32_e32 v143, v143, v226
	v_add_f32_e32 v210, v210, v234
	v_lshlrev_b32_e32 v227, 16, v55
	v_lshlrev_b32_e32 v235, 16, v63
	v_add_f32_e32 v143, v143, v54
	v_add_f32_e32 v210, v210, v62
	v_and_b32_e32 v55, 0xffff0000, v55
	v_and_b32_e32 v63, 0xffff0000, v63
	v_add_f32_e32 v143, v143, v227
	v_add_f32_e32 v210, v210, v235
	v_add_f32_e32 v143, v143, v55
	v_add_f32_e32 v210, v210, v63
	ds_bpermute_b32 v153, v1, v143
	ds_bpermute_b32 v211, v1, v210
	v_lshlrev_b32_e32 v228, 16, v56
	v_lshlrev_b32_e32 v236, 16, v64
	v_and_b32_e32 v56, 0xffff0000, v56
	s_waitcnt lgkmcnt(1)
	v_add_f32_e32 v143, v143, v153
	s_waitcnt lgkmcnt(0)
	v_add_f32_e32 v210, v210, v211
	ds_bpermute_b32 v153, v3, v143
	ds_bpermute_b32 v211, v3, v210
	v_and_b32_e32 v64, 0xffff0000, v64
	v_lshlrev_b32_e32 v229, 16, v57
	v_lshlrev_b32_e32 v237, 16, v65
	s_waitcnt lgkmcnt(1)
	v_add_f32_e32 v143, v143, v153
	s_waitcnt lgkmcnt(0)
	v_add_f32_e32 v210, v210, v211
	ds_bpermute_b32 v153, v6, v143
	ds_bpermute_b32 v211, v6, v210
	v_and_b32_e32 v57, 0xffff0000, v57
	v_and_b32_e32 v65, 0xffff0000, v65
	v_lshlrev_b32_e32 v230, 16, v58
	s_waitcnt lgkmcnt(1)
	v_add_f32_e32 v143, v143, v153
	s_waitcnt lgkmcnt(0)
	v_add_f32_e32 v210, v210, v211
	ds_bpermute_b32 v153, v7, v143
	ds_bpermute_b32 v211, v7, v210
	v_lshlrev_b32_e32 v238, 16, v66
	v_and_b32_e32 v58, 0xffff0000, v58
	v_and_b32_e32 v66, 0xffff0000, v66
	s_waitcnt lgkmcnt(1)
	v_add_f32_e32 v143, v143, v153
	s_waitcnt lgkmcnt(0)
	v_add_f32_e32 v210, v210, v211
	ds_bpermute_b32 v153, v8, v143
	ds_bpermute_b32 v211, v8, v210
	v_lshlrev_b32_e32 v231, 16, v59
	v_lshlrev_b32_e32 v239, 16, v67
	v_and_b32_e32 v59, 0xffff0000, v59
	s_waitcnt lgkmcnt(1)
	v_add_f32_e32 v143, v143, v153
	s_waitcnt lgkmcnt(0)
	v_add_f32_e32 v210, v210, v211
	ds_bpermute_b32 v153, v9, v143
	ds_bpermute_b32 v211, v9, v210
	v_and_b32_e32 v67, 0xffff0000, v67
	s_waitcnt lgkmcnt(1)
	v_add_f32_e32 v143, v143, v153
	s_waitcnt lgkmcnt(0)
	v_add_f32_e32 v210, v210, v211
	v_fmac_f32_e32 v52, 0xbb000000, v143
	v_fmac_f32_e32 v60, 0xbb000000, v210
	v_fmac_f32_e32 v224, 0xbb000000, v143
	v_fmac_f32_e32 v232, 0xbb000000, v210
	v_fmac_f32_e32 v225, 0xbb000000, v143
	v_fmac_f32_e32 v233, 0xbb000000, v210
	v_fmac_f32_e32 v53, 0xbb000000, v143
	v_fmac_f32_e32 v61, 0xbb000000, v210
	v_fmac_f32_e32 v226, 0xbb000000, v143
	v_fmac_f32_e32 v234, 0xbb000000, v210
	v_fmac_f32_e32 v54, 0xbb000000, v143
	v_fmac_f32_e32 v62, 0xbb000000, v210
	v_fmac_f32_e32 v227, 0xbb000000, v143
	v_fmac_f32_e32 v235, 0xbb000000, v210
	v_fmac_f32_e32 v55, 0xbb000000, v143
	v_fmac_f32_e32 v63, 0xbb000000, v210
	v_mul_f32_e32 v143, v52, v52
	v_mul_f32_e32 v210, v60, v60
	v_fmac_f32_e32 v143, v224, v224
	v_fmac_f32_e32 v210, v232, v232
	v_fmac_f32_e32 v143, v225, v225
	v_fmac_f32_e32 v210, v233, v233
	v_fmac_f32_e32 v143, v53, v53
	v_fmac_f32_e32 v210, v61, v61
	v_fmac_f32_e32 v143, v226, v226
	v_fmac_f32_e32 v210, v234, v234
	v_fmac_f32_e32 v143, v54, v54
	v_fmac_f32_e32 v210, v62, v62
	v_fmac_f32_e32 v143, v227, v227
	v_fmac_f32_e32 v210, v235, v235
	v_fmac_f32_e32 v143, v55, v55
	v_fmac_f32_e32 v210, v63, v63
	ds_bpermute_b32 v153, v1, v143
	ds_bpermute_b32 v211, v1, v210
	s_waitcnt lgkmcnt(1)
	v_add_f32_e32 v143, v143, v153
	s_waitcnt lgkmcnt(0)
	v_add_f32_e32 v210, v210, v211
	ds_bpermute_b32 v153, v3, v143
	ds_bpermute_b32 v211, v3, v210
	s_waitcnt lgkmcnt(1)
	v_add_f32_e32 v143, v143, v153
	s_waitcnt lgkmcnt(0)
	v_add_f32_e32 v210, v210, v211
	ds_bpermute_b32 v153, v6, v143
	ds_bpermute_b32 v211, v6, v210
	s_waitcnt lgkmcnt(1)
	v_add_f32_e32 v143, v143, v153
	s_waitcnt lgkmcnt(0)
	v_add_f32_e32 v210, v210, v211
	ds_bpermute_b32 v153, v7, v143
	ds_bpermute_b32 v211, v7, v210
	s_waitcnt lgkmcnt(1)
	v_add_f32_e32 v143, v143, v153
	s_waitcnt lgkmcnt(0)
	v_add_f32_e32 v210, v210, v211
	ds_bpermute_b32 v153, v8, v143
	ds_bpermute_b32 v211, v8, v210
	s_waitcnt lgkmcnt(1)
	v_add_f32_e32 v143, v143, v153
	s_waitcnt lgkmcnt(0)
	v_add_f32_e32 v210, v210, v211
	ds_bpermute_b32 v153, v9, v143
	ds_bpermute_b32 v211, v9, v210
	s_waitcnt lgkmcnt(1)
	v_add_f32_e32 v143, v143, v153
	s_waitcnt lgkmcnt(0)
; __device__ __forceinline__ unsigned pk2(float lo, float hi) { unsigned r; asm("v_cvt_pk_bf16_f32 %0, %1, %2" : "=v"(r) : "v"(lo), "v"(hi)); return r; }
; __device__ __forceinline__ void p4_gn_gate(Frame& F) {
;     ...
;         const int r = t >> 3, h = t & 7; const size_t off = (size_t)r * HV + h * DV + 8 * F.lane;
;         const u32x4 ov = *(const u32x4*)(O + off), gv = *(const u32x4*)(G + off);
;     ...
;         const float rstd = 1.0f / sqrtf(wave_sum(q) * (1.0f / DV) + 1e-6f);
;         const f32x4 w0 = *(const f32x4*)(F.ret_gn_g + h * DV + 8 * F.lane), w1 = *(const f32x4*)(F.ret_gn_g + h * DV + 8 * F.lane + 4);
;         float y[8];
; #pragma unroll
;         for (int i = 0; i < 4; ++i) { y[i] = g[i] * (o[i] * rstd * w0[i]); y[i + 4] = g[i + 4] * (o[i + 4] * rstd * w1[i]); }
;         if (FP8O) { u32x2 out; out.x = pk4_fp8(y[0] * S_A2, y[1] * S_A2, y[2] * S_A2, y[3] * S_A2); out.y = pk4_fp8(y[4] * S_A2, y[5] * S_A2, y[6] * S_A2, y[7] * S_A2); *(u32x2*)((unsigned char*)A2 + off) = out; }
;         else { u32x4 out; out.x = pk2(y[0], y[1]); out.y = pk2(y[2], y[3]); out.z = pk2(y[4], y[5]); out.w = pk2(y[6], y[7]); *(u32x4*)(A2 + off) = out; }
;     }
	v_add_f32_e32 v210, v210, v211
	v_fmamk_f32 v143, v143, 0x3b000000, v10
	v_mul_f32_e32 v153, 0x4f800000, v143
	v_cmp_gt_f32_e32 vcc, s19, v143
	s_nop 1
	v_cndmask_b32_e32 v143, v143, v153, vcc
	v_sqrt_f32_e32 v153, v143
	s_nop 0
	v_add_u32_e32 v155, -1, v153
	v_add_u32_e32 v159, 1, v153
	v_fma_f32 v221, -v155, v153, v143
	v_fma_f32 v46, -v159, v153, v143
	v_cmp_ge_f32_e64 s[56:57], 0, v221
	s_nop 1
	v_cndmask_b32_e64 v153, v153, v155, s[56:57]
	v_cmp_lt_f32_e64 s[56:57], 0, v46
	s_nop 1
	v_cndmask_b32_e64 v153, v153, v159, s[56:57]
	v_mul_f32_e32 v155, 0x37800000, v153
	v_cndmask_b32_e32 v153, v153, v155, vcc
	v_cmp_class_f32_e32 vcc, v143, v11
	s_nop 1
	v_cndmask_b32_e32 v143, v153, v143, vcc
	v_div_scale_f32 v153, s[56:57], v143, v143, 1.0
	v_rcp_f32_e32 v159, v153
	v_div_scale_f32 v155, vcc, 1.0, v143, 1.0
	v_fma_f32 v221, -v153, v159, 1.0
	v_fmac_f32_e32 v159, v221, v159
	v_mul_f32_e32 v221, v155, v159
	v_fma_f32 v46, -v153, v221, v155
	v_fmac_f32_e32 v221, v46, v159
	v_fma_f32 v153, -v153, v221, v155
	v_div_fmas_f32 v153, v153, v159, v221
	v_div_fixup_f32 v143, v153, v143, 1.0
	v_fmamk_f32 v210, v210, 0x3b000000, v10
	v_mul_f32_e32 v211, 0x4f800000, v210
	v_cmp_gt_f32_e32 vcc, s19, v210
	s_nop 1
	v_cndmask_b32_e32 v210, v210, v211, vcc
	v_sqrt_f32_e32 v211, v210
	s_nop 0
	v_add_u32_e32 v192, -1, v211
	v_add_u32_e32 v193, 1, v211
	v_fma_f32 v222, -v192, v211, v210
	v_fma_f32 v223, -v193, v211, v210
	v_cmp_ge_f32_e64 s[58:59], 0, v222
	s_nop 1
	v_cndmask_b32_e64 v211, v211, v192, s[58:59]
	v_cmp_lt_f32_e64 s[58:59], 0, v223
	s_nop 1
	v_cndmask_b32_e64 v211, v211, v193, s[58:59]
	v_mul_f32_e32 v192, 0x37800000, v211
	v_cndmask_b32_e32 v211, v211, v192, vcc
	v_cmp_class_f32_e32 vcc, v210, v11
	s_nop 1
	v_cndmask_b32_e32 v210, v211, v210, vcc
	v_div_scale_f32 v211, s[58:59], v210, v210, 1.0
	v_rcp_f32_e32 v193, v211
	v_div_scale_f32 v192, vcc, 1.0, v210, 1.0
	v_fma_f32 v222, -v211, v193, 1.0
	v_fmac_f32_e32 v193, v222, v193
	v_mul_f32_e32 v222, v192, v193
	v_fma_f32 v223, -v211, v222, v192
	v_fmac_f32_e32 v222, v223, v193
	v_fma_f32 v211, -v211, v222, v192
	v_div_fmas_f32 v211, v211, v193, v222
	v_div_fixup_f32 v210, v211, v210, 1.0
	v_mul_f32_e32 v224, v224, v143
	v_mul_f32_e32 v232, v232, v210
	v_mul_f32_e32 v52, v52, v143
	v_mul_f32_e32 v60, v60, v210
	v_mul_f32_e32 v226, v226, v143
	v_mul_f32_e32 v234, v234, v210
	v_mul_f32_e32 v54, v54, v143
	v_mul_f32_e32 v62, v62, v210
	v_mul_f32_e32 v224, v212, v224
	v_mul_f32_e32 v232, v212, v232
	v_mul_f32_e32 v52, v213, v52
	v_mul_f32_e32 v60, v213, v60
	v_mul_f32_e32 v226, v216, v226
	v_mul_f32_e32 v234, v216, v234
	v_mul_f32_e32 v54, v217, v54
	v_mul_f32_e32 v62, v217, v62
	v_mul_f32_e32 v224, v224, v228
	v_mul_f32_e32 v232, v232, v236
	v_mul_f32_e32 v52, v52, v56
	v_mul_f32_e32 v60, v60, v64
	v_mul_f32_e32 v226, v226, v230
	v_mul_f32_e32 v234, v234, v238
	v_mul_f32_e32 v54, v54, v58
	v_mul_f32_e32 v62, v62, v66
	v_mul_f32_e32 v224, 0x41000000, v224
	v_mul_f32_e32 v232, 0x41000000, v232
	v_mul_f32_e32 v52, 0x41000000, v52
	v_mul_f32_e32 v60, 0x41000000, v60
	v_mul_f32_e32 v226, 0x41000000, v226
	v_mul_f32_e32 v234, 0x41000000, v234
	v_mul_f32_e32 v54, 0x41000000, v54
	v_mul_f32_e32 v62, 0x41000000, v62
	v_med3_f32 v224, v224, s20, v12
	v_med3_f32 v232, v232, s20, v12
	v_med3_f32 v52, v52, s20, v12
	v_med3_f32 v60, v60, s20, v12
	v_med3_f32 v226, v226, s20, v12
	v_med3_f32 v234, v234, s20, v12
	v_med3_f32 v54, v54, s20, v12
	v_med3_f32 v62, v62, s20, v12
	v_cvt_pk_fp8_f32 v44, v224, v52
	v_cvt_pk_fp8_f32 v70, v232, v60
	v_cvt_pk_fp8_f32 v45, v226, v54
	v_cvt_pk_fp8_f32 v71, v234, v62
	v_mul_f32_e32 v225, v225, v143
	v_mul_f32_e32 v233, v233, v210
	v_mul_f32_e32 v53, v53, v143
	v_mul_f32_e32 v61, v61, v210
	v_mul_f32_e32 v227, v227, v143
	v_mul_f32_e32 v235, v235, v210
	v_mul_f32_e32 v55, v55, v143
	v_mul_f32_e32 v63, v63, v210
	v_mul_f32_e32 v225, v214, v225
	v_mul_f32_e32 v233, v214, v233
	v_mul_f32_e32 v53, v215, v53
	v_mul_f32_e32 v61, v215, v61
	v_mul_f32_e32 v227, v218, v227
	v_mul_f32_e32 v235, v218, v235
	v_mul_f32_e32 v55, v219, v55
	v_mul_f32_e32 v63, v219, v63
	v_mul_f32_e32 v225, v225, v229
	v_mul_f32_e32 v233, v233, v237
	v_mul_f32_e32 v53, v53, v57
	v_mul_f32_e32 v61, v61, v65
	v_mul_f32_e32 v227, v227, v231
	v_mul_f32_e32 v235, v235, v239
	v_mul_f32_e32 v55, v55, v59
	v_mul_f32_e32 v63, v63, v67
	v_mul_f32_e32 v225, 0x41000000, v225
	v_mul_f32_e32 v233, 0x41000000, v233
	v_mul_f32_e32 v53, 0x41000000, v53
	v_mul_f32_e32 v61, 0x41000000, v61
	v_mul_f32_e32 v227, 0x41000000, v227
	v_mul_f32_e32 v235, 0x41000000, v235
	v_mul_f32_e32 v55, 0x41000000, v55
	v_mul_f32_e32 v63, 0x41000000, v63
	v_med3_f32 v225, v225, s20, v12
	v_med3_f32 v233, v233, s20, v12
	v_med3_f32 v53, v53, s20, v12
	v_med3_f32 v61, v61, s20, v12
	v_med3_f32 v227, v227, s20, v12
	v_med3_f32 v235, v235, s20, v12
	v_med3_f32 v55, v55, s20, v12
	v_med3_f32 v63, v63, s20, v12
	v_cvt_pk_fp8_f32 v44, v225, v53 op_sel:[0,0,1]
	v_cvt_pk_fp8_f32 v70, v233, v61 op_sel:[0,0,1]
	v_cvt_pk_fp8_f32 v45, v227, v55 op_sel:[0,0,1]
	v_cvt_pk_fp8_f32 v71, v235, v63 op_sel:[0,0,1]
	s_add_i32 s10, s10, s16
	s_add_i32 s10, s10, s16
	global_store_dwordx2 v15, v[44:45], s[46:47]
	global_store_dwordx2 v15, v[70:71], s[50:51]
	s_min_u32 s0, s1, 0x11fff
	s_lshr_b32 s0, s0, 3
	s_lshl_b32 s0, s0, 13
	s_add_u32 s32, s4, s0
	s_addc_u32 s33, s5, 0
	s_add_u32 s40, s6, s0
	s_addc_u32 s41, s7, 0
	global_load_dwordx4 v[52:55], v13, s[32:33] nt
	global_load_dwordx4 v[56:59], v13, s[40:41] nt
	s_add_i32 s1, s1, s16
	s_min_u32 s0, s1, 0x11fff
	s_lshr_b32 s0, s0, 3
	s_lshl_b32 s0, s0, 13
	s_add_u32 s32, s4, s0
	s_addc_u32 s33, s5, 0
	s_add_u32 s40, s6, s0
	s_addc_u32 s41, s7, 0
	global_load_dwordx4 v[60:63], v13, s[32:33] nt
	global_load_dwordx4 v[64:67], v13, s[40:41] nt
	s_add_i32 s1, s1, s16
	s_branch .Lp4_loop
	s_nop 0
	s_nop 0
	s_nop 0
	s_nop 0
	s_nop 0
	s_nop 0
	s_nop 0
	s_nop 0
	s_nop 0
	s_nop 0
	s_nop 0
	s_nop 0
	s_nop 0
	s_nop 0
	s_nop 0
	s_nop 0
	s_nop 0
	s_nop 0
	s_nop 0
	s_nop 0
	s_nop 0
	s_nop 0
	s_nop 0
	s_nop 0
	s_nop 0
